# attention work items remapped so the 8 workgroups of a head share an XCD (K/V reuse in L2)
# baseline (speedup 1.0000x reference)
.LBB0_1712:
	s_and_b32 s0, s53, 7
	s_lshl_b32 s0, s0, 5
	s_bfe_u32 s1, s53, 0x20003
	s_lshl_b32 s1, s1, 3
	s_or_b32 s0, s0, s1
	s_lshr_b32 s1, s53, 5
	s_or_b32 s4, s0, s1
	s_ashr_i32 s0, s4, 3
	s_and_b32 s80, s4, 7
	s_ashr_i32 s1, s0, 31
	s_xor_b32 s81, s80, 15
	s_ashr_i32 s4, s4, 7
	s_lshl_b64 s[8:9], s[0:1], 13
	v_readlane_b32 s5, v237, 26
	v_mov_b32_e32 v4, v236
	s_add_u32 s54, s5, s8
	v_readlane_b32 s5, v237, 36
	s_addc_u32 s55, s5, s9
	v_ashrrev_i32_e32 v5, 31, v4
	v_lshl_add_u64 v[0:1], v[4:5], 4, s[54:55]
	s_barrier
	global_load_dwordx4 v[0:3], v[0:1], off
	s_lshl_b64 s[12:13], s[0:1], 20
	s_add_u32 s50, s36, s12
	s_addc_u32 s51, s37, s13
	s_add_u32 s56, s96, s12
	v_readlane_b32 s1, v237, 20
	s_addc_u32 s57, s1, s13
	v_ashrrev_i32_e32 v10, 3, v4
	s_add_u32 s48, s50, 0x2000
	v_ashrrev_i32_e32 v74, 1, v4
	v_ashrrev_i32_e32 v11, 31, v10
	s_addc_u32 s49, s51, 0
	s_ashr_i32 s5, s4, 31
	v_lshlrev_b32_e32 v6, 4, v4
	v_bfi_b32 v146, s26, v74, v4
	v_lshlrev_b64 v[8:9], 13, v[10:11]
	s_lshl_b32 s1, s81, 8
	s_lshl_b32 s0, s0, 7
	s_lshl_b64 s[62:63], s[4:5], 12
	v_and_b32_e32 v144, 0x70, v6
	v_ashrrev_i32_e32 v147, 31, v146
	v_lshl_add_u64 v[12:13], s[56:57], 0, v[8:9]
	s_and_b32 s4, s0, 0x780
	s_or_b32 s0, s62, s1
	s_mov_b32 s1, s63
	v_lshl_add_u64 v[50:51], v[12:13], 0, v[144:145]
	v_lshl_add_u64 v[12:13], s[0:1], 0, v[146:147]
	v_lshlrev_b64 v[14:15], 12, v[12:13]
	v_bfe_u32 v5, v4, 5, 1
	s_lshl_b32 s42, s4, 1
	v_lshl_add_u64 v[14:15], s[38:39], 0, v[14:15]
	v_lshlrev_b32_e32 v144, 4, v5
	v_lshl_add_u64 v[14:15], v[14:15], 0, s[42:43]
	v_add_u32_e32 v7, s78, v6
	v_lshl_add_u64 v[52:53], v[14:15], 0, v[144:145]
	v_lshlrev_b32_e32 v75, 5, v5
	v_add_co_u32_e32 v58, vcc, s85, v50
	s_cmp_lg_u32 s80, 7
	s_nop 0
	v_addc_co_u32_e32 v59, vcc, 0, v51, vcc
	v_cmp_lt_i32_e32 vcc, v156, v157
	s_cselect_b64 s[66:67], -1, 0
	s_cmp_eq_u32 s80, 7
	s_waitcnt vmcnt(0)
	ds_write_b128 v7, v[0:3]
	s_waitcnt lgkmcnt(0)
	s_barrier
	global_load_dwordx4 v[0:3], v[52:53], off
	global_load_dwordx4 v[14:17], v[52:53], off offset:32
	global_load_dwordx4 v[18:21], v[52:53], off offset:64
	global_load_dwordx4 v[22:25], v[52:53], off offset:96
	global_load_dwordx4 v[26:29], v[52:53], off offset:128
	global_load_dwordx4 v[30:33], v75, s[82:83]
	global_load_dwordx4 v[34:37], v75, s[82:83] offset:16
	global_load_dwordx4 v[38:41], v75, s[82:83] offset:64
	global_load_dwordx4 v[42:45], v75, s[82:83] offset:80
	global_load_dwordx4 v[46:49], v75, s[82:83] offset:128
	global_load_dwordx4 v[70:73], v75, s[82:83] offset:144
	global_load_dwordx4 v[76:79], v75, s[82:83] offset:208
	global_load_dwordx4 v[80:83], v75, s[82:83] offset:192
	global_load_dwordx4 v[84:87], v75, s[82:83] offset:272
	global_load_dwordx4 v[88:91], v75, s[82:83] offset:256
	v_ashrrev_i32_e32 v7, 31, v6
	v_lshl_add_u64 v[54:55], s[50:51], 0, v[6:7]
	v_lshl_add_u64 v[56:57], s[48:49], 0, v[6:7]
	global_load_dwordx4 v[100:103], v[54:55], off
	global_load_dwordx4 v[96:99], v[56:57], off
	global_load_dwordx4 v[104:107], v[50:51], off
	global_load_dwordx4 v[108:111], v[58:59], off
	global_load_dwordx4 v[92:95], v[52:53], off offset:160
	global_load_dwordx4 v[112:115], v75, s[82:83] offset:336
	global_load_dwordx4 v[116:119], v75, s[82:83] offset:320
	global_load_dwordx4 v[120:123], v75, s[82:83] offset:400
	global_load_dwordx4 v[124:127], v75, s[82:83] offset:384
	global_load_dwordx4 v[128:131], v[52:53], off offset:192
	global_load_dwordx4 v[132:135], v[52:53], off offset:224
	global_load_dwordx4 v[136:139], v75, s[82:83] offset:464
	global_load_dwordx4 v[140:143], v75, s[82:83] offset:448
	s_waitcnt vmcnt(27)
	v_lshlrev_b32_e32 v58, 16, v0
	v_and_b32_e32 v59, 0xffff0000, v0
	v_lshlrev_b32_e32 v50, 16, v2
	v_and_b32_e32 v51, 0xffff0000, v2
	v_lshlrev_b32_e32 v64, 16, v1
	v_and_b32_e32 v65, 0xffff0000, v1
	v_lshlrev_b32_e32 v0, 16, v3
	v_and_b32_e32 v1, 0xffff0000, v3
	s_waitcnt vmcnt(26)
	v_lshlrev_b32_e32 v148, 16, v14
	v_and_b32_e32 v149, 0xffff0000, v14
	v_lshlrev_b32_e32 v150, 16, v15
	v_and_b32_e32 v151, 0xffff0000, v15
	v_lshlrev_b32_e32 v14, 16, v17
	v_and_b32_e32 v15, 0xffff0000, v17
	s_waitcnt vmcnt(25)
	v_lshlrev_b32_e32 v152, 16, v18
	v_and_b32_e32 v153, 0xffff0000, v18
	v_lshlrev_b32_e32 v170, 16, v19
	v_and_b32_e32 v171, 0xffff0000, v19
	v_lshlrev_b32_e32 v18, 16, v21
	v_and_b32_e32 v19, 0xffff0000, v21
	s_waitcnt vmcnt(24)
	v_lshlrev_b32_e32 v172, 16, v22
	v_and_b32_e32 v173, 0xffff0000, v22
	s_waitcnt vmcnt(22)
	v_pk_mul_f32 v[60:61], v[30:31], v[58:59]
	v_pk_mul_f32 v[30:31], v[50:51], v[50:51]
	v_lshlrev_b32_e32 v22, 16, v23
	v_and_b32_e32 v23, 0xffff0000, v23
	s_waitcnt vmcnt(21)
	v_pk_mul_f32 v[62:63], v[34:35], v[50:51]
	v_pk_mul_f32 v[66:67], v[32:33], v[64:65]
	v_pk_mul_f32 v[32:33], v[0:1], v[0:1]
	s_waitcnt vmcnt(20)
	v_pk_mul_f32 v[50:51], v[38:39], v[148:149]
	s_waitcnt vmcnt(19)
	v_pk_mul_f32 v[56:57], v[44:45], v[14:15]
	s_waitcnt vmcnt(18)
	v_pk_mul_f32 v[38:39], v[46:47], v[152:153]
	v_pk_mul_f32 v[44:45], v[48:49], v[170:171]
	v_pk_mul_f32 v[48:49], v[18:19], v[18:19]
	s_waitcnt vmcnt(17)
	v_pk_mul_f32 v[46:47], v[72:73], v[18:19]
	s_waitcnt vmcnt(15)
	v_pk_mul_f32 v[18:19], v[80:81], v[172:173]
	v_pk_fma_f32 v[80:81], v[58:59], v[58:59], v[30:31]
	v_lshlrev_b32_e32 v2, 16, v16
	v_and_b32_e32 v3, 0xffff0000, v16
	v_lshlrev_b32_e32 v16, 16, v20
	v_and_b32_e32 v17, 0xffff0000, v20
	v_lshlrev_b32_e32 v20, 16, v24
	v_and_b32_e32 v21, 0xffff0000, v24
	v_lshlrev_b32_e32 v174, 16, v25
	v_and_b32_e32 v175, 0xffff0000, v25
	v_pk_mul_f32 v[24:25], v[82:83], v[22:23]
	v_pk_fma_f32 v[82:83], v[64:65], v[64:65], v[32:33]
	v_add_f32_e32 v11, v80, v81
	v_lshlrev_b32_e32 v178, 16, v28
	v_and_b32_e32 v179, 0xffff0000, v28
	v_pk_mul_f32 v[34:35], v[2:3], v[2:3]
	v_add_f32_e32 v11, v82, v11
	v_pk_mul_f32 v[52:53], v[42:43], v[2:3]
	s_waitcnt vmcnt(14)
	v_pk_mul_f32 v[2:3], v[84:85], v[178:179]
	v_pk_fma_f32 v[84:85], v[148:149], v[148:149], v[34:35]
	v_add_f32_e32 v11, v83, v11
	v_lshlrev_b32_e32 v28, 16, v29
	v_and_b32_e32 v29, 0xffff0000, v29
	v_pk_mul_f32 v[68:69], v[36:37], v[0:1]
	v_pk_mul_f32 v[36:37], v[14:15], v[14:15]
	v_add_f32_e32 v11, v11, v84
	v_pk_mul_f32 v[54:55], v[40:41], v[150:151]
	v_pk_mul_f32 v[42:43], v[16:17], v[16:17]
	v_pk_mul_f32 v[40:41], v[70:71], v[16:17]
	v_pk_mul_f32 v[16:17], v[86:87], v[28:29]
	v_pk_fma_f32 v[86:87], v[150:151], v[150:151], v[36:37]
	v_add_f32_e32 v11, v85, v11
	v_lshlrev_b32_e32 v176, 16, v26
	v_and_b32_e32 v177, 0xffff0000, v26
	v_add_f32_e32 v11, v86, v11
	s_waitcnt vmcnt(13)
	v_pk_mul_f32 v[0:1], v[88:89], v[176:177]
	v_pk_fma_f32 v[88:89], v[152:153], v[152:153], v[42:43]
	v_add_f32_e32 v11, v87, v11
	v_lshlrev_b32_e32 v180, 16, v27
	v_and_b32_e32 v181, 0xffff0000, v27
	v_add_f32_e32 v11, v88, v11
	v_pk_mul_f32 v[14:15], v[90:91], v[180:181]
	v_pk_fma_f32 v[90:91], v[170:171], v[170:171], v[48:49]
	v_add_f32_e32 v11, v89, v11
	v_pk_mul_f32 v[70:71], v[20:21], v[20:21]
	v_add_f32_e32 v11, v90, v11
	v_pk_fma_f32 v[148:149], v[172:173], v[172:173], v[70:71]
	v_add_f32_e32 v11, v91, v11
	v_pk_mul_f32 v[72:73], v[174:175], v[174:175]
	v_add_f32_e32 v11, v148, v11
	v_pk_fma_f32 v[72:73], v[22:23], v[22:23], v[72:73]
	v_add_f32_e32 v11, v149, v11
	v_pk_mul_f32 v[20:21], v[76:77], v[20:21]
	v_pk_mul_f32 v[76:77], v[178:179], v[178:179]
	v_add_f32_e32 v11, v72, v11
	v_pk_fma_f32 v[76:77], v[176:177], v[176:177], v[76:77]
	v_add_f32_e32 v11, v73, v11
	v_pk_mul_f32 v[26:27], v[78:79], v[174:175]
	v_pk_mul_f32 v[78:79], v[28:29], v[28:29]
	v_add_f32_e32 v11, v76, v11
	v_pk_fma_f32 v[78:79], v[180:181], v[180:181], v[78:79]
	v_add_f32_e32 v11, v77, v11
	v_add_f32_e32 v11, v78, v11
	v_add_u32_e32 v77, s78, v75
	v_add_f32_e32 v11, v79, v11
	ds_read_b128 v[78:81], v77
	ds_read_b128 v[82:85], v77 offset:16
	s_waitcnt vmcnt(8)
	v_lshlrev_b32_e32 v30, 16, v94
	v_and_b32_e32 v31, 0xffff0000, v94
	v_lshlrev_b32_e32 v28, 16, v92
	v_and_b32_e32 v29, 0xffff0000, v92
	v_pk_mul_f32 v[32:33], v[30:31], v[30:31]
	v_cndmask_b32_e32 v75, v155, v156, vcc
	s_waitcnt vmcnt(6)
	v_pk_mul_f32 v[22:23], v[116:117], v[28:29]
	v_pk_fma_f32 v[116:117], v[28:29], v[28:29], v[32:33]
	v_lshlrev_b32_e32 v32, 16, v95
	v_and_b32_e32 v33, 0xffff0000, v95
	v_lshlrev_b32_e32 v169, 2, v75
	s_waitcnt lgkmcnt(1)
	v_fma_f32 v75, v60, v78, 0
	v_pk_mul_f32 v[28:29], v[112:113], v[30:31]
	v_lshlrev_b32_e32 v30, 16, v93
	v_and_b32_e32 v31, 0xffff0000, v93
	v_pk_mul_f32 v[34:35], v[32:33], v[32:33]
	v_add_f32_e32 v11, v116, v11
	s_waitcnt lgkmcnt(0)
	v_fmac_f32_e32 v75, v62, v82
	v_pk_fma_f32 v[92:93], v[30:31], v[30:31], v[34:35]
	v_add_f32_e32 v11, v117, v11
	v_fmac_f32_e32 v75, v61, v79
	v_add_f32_e32 v11, v92, v11
	v_fmac_f32_e32 v75, v63, v83
	v_add_f32_e32 v11, v93, v11
	v_fmac_f32_e32 v75, v66, v80
	ds_read_b128 v[86:89], v77 offset:64
	ds_read_b128 v[90:93], v77 offset:80
	v_fmac_f32_e32 v75, v68, v84
	v_fmac_f32_e32 v75, v67, v81
	v_fmac_f32_e32 v75, v69, v85
	s_waitcnt lgkmcnt(1)
	v_fmac_f32_e32 v75, v50, v86
	s_waitcnt lgkmcnt(0)
	v_fmac_f32_e32 v75, v52, v90
	v_fmac_f32_e32 v75, v51, v87
	v_fmac_f32_e32 v75, v53, v91
	v_fmac_f32_e32 v75, v54, v88
	ds_read_b128 v[78:81], v77 offset:128
	ds_read_b128 v[82:85], v77 offset:144
	v_fmac_f32_e32 v75, v56, v92
	v_fmac_f32_e32 v75, v55, v89
	v_fmac_f32_e32 v75, v57, v93
	s_waitcnt lgkmcnt(1)
	v_fmac_f32_e32 v75, v38, v78
	s_waitcnt lgkmcnt(0)
	v_fmac_f32_e32 v75, v40, v82
	v_fmac_f32_e32 v75, v39, v79
	v_fmac_f32_e32 v75, v41, v83
	v_fmac_f32_e32 v75, v44, v80
	ds_read_b128 v[86:89], v77 offset:192
	ds_read_b128 v[90:93], v77 offset:208
	v_fmac_f32_e32 v75, v46, v84
	v_fmac_f32_e32 v75, v45, v81
	v_fmac_f32_e32 v75, v47, v85
	s_waitcnt lgkmcnt(1)
	v_fmac_f32_e32 v75, v18, v86
	s_waitcnt lgkmcnt(0)
	v_fmac_f32_e32 v75, v20, v90
	v_fmac_f32_e32 v75, v19, v87
	v_fmac_f32_e32 v75, v21, v91
	v_fmac_f32_e32 v75, v24, v88
	ds_read_b128 v[78:81], v77 offset:256
	ds_read_b128 v[82:85], v77 offset:272
	v_fmac_f32_e32 v75, v26, v92
	v_fmac_f32_e32 v75, v25, v89
	v_fmac_f32_e32 v75, v27, v93
	s_waitcnt lgkmcnt(1)
	v_fmac_f32_e32 v75, v0, v78
	s_waitcnt lgkmcnt(0)
	v_fmac_f32_e32 v75, v2, v82
	v_fmac_f32_e32 v75, v1, v79
	v_fmac_f32_e32 v75, v3, v83
	v_fmac_f32_e32 v75, v14, v80
	ds_read_b128 v[86:89], v77 offset:320
	ds_read_b128 v[90:93], v77 offset:336
	v_fmac_f32_e32 v75, v16, v84
	v_fmac_f32_e32 v75, v15, v81
	v_fmac_f32_e32 v75, v17, v85
	s_waitcnt lgkmcnt(1)
	v_fmac_f32_e32 v75, v22, v86
	s_waitcnt lgkmcnt(0)
	v_fmac_f32_e32 v75, v28, v90
	v_fmac_f32_e32 v75, v23, v87
	v_pk_mul_f32 v[42:43], v[118:119], v[30:31]
	v_fmac_f32_e32 v75, v29, v91
	v_pk_mul_f32 v[48:49], v[114:115], v[32:33]
	v_fmac_f32_e32 v75, v42, v88
	ds_read_b128 v[78:81], v77 offset:384
	ds_read_b128 v[82:85], v77 offset:400
	v_fmac_f32_e32 v75, v48, v92
	s_waitcnt vmcnt(3)
	v_lshlrev_b32_e32 v30, 16, v128
	v_and_b32_e32 v31, 0xffff0000, v128
	v_fmac_f32_e32 v75, v43, v89
	v_pk_mul_f32 v[32:33], v[124:125], v[30:31]
	v_lshlrev_b32_e32 v34, 16, v130
	v_and_b32_e32 v35, 0xffff0000, v130
	v_fmac_f32_e32 v75, v49, v93
	v_pk_mul_f32 v[36:37], v[34:35], v[34:35]
	v_pk_mul_f32 v[34:35], v[120:121], v[34:35]
	s_waitcnt lgkmcnt(1)
	v_fmac_f32_e32 v75, v32, v78
	s_waitcnt lgkmcnt(0)
	v_fmac_f32_e32 v75, v34, v82
	v_pk_fma_f32 v[94:95], v[30:31], v[30:31], v[36:37]
	v_lshlrev_b32_e32 v31, 16, v129
	v_lshlrev_b32_e32 v30, 16, v131
	v_mov_b32_e32 v36, v122
	v_mov_b32_e32 v37, v126
	v_fmac_f32_e32 v75, v33, v79
	v_pk_mul_f32 v[36:37], v[36:37], v[30:31]
	v_and_b32_e32 v58, 0xffff0000, v131
	v_fmac_f32_e32 v75, v35, v83
	v_and_b32_e32 v59, 0xffff0000, v129
	v_mov_b32_e32 v70, v58
	v_mov_b32_e32 v71, v30
	v_mov_b32_e32 v126, v123
	v_fmac_f32_e32 v75, v37, v80
	ds_read_b128 v[86:89], v77 offset:448
	ds_read_b128 v[90:93], v77 offset:464
	v_mov_b32_e32 v64, v59
	v_mov_b32_e32 v65, v31
	v_pk_mul_f32 v[30:31], v[70:71], v[70:71]
	v_pk_mul_f32 v[58:59], v[126:127], v[58:59]
	v_fmac_f32_e32 v75, v36, v84
	v_pk_fma_f32 v[112:113], v[64:65], v[64:65], v[30:31]
	s_waitcnt vmcnt(2)
	v_lshlrev_b32_e32 v65, 16, v132
	v_lshlrev_b32_e32 v64, 16, v134
	s_waitcnt vmcnt(1)
	v_mov_b32_e32 v30, v136
	s_waitcnt vmcnt(0)
	v_mov_b32_e32 v31, v140
	v_and_b32_e32 v70, 0xffff0000, v134
	v_fmac_f32_e32 v75, v59, v81
	v_pk_mul_f32 v[30:31], v[30:31], v[64:65]
	v_and_b32_e32 v71, 0xffff0000, v132
	v_mov_b32_e32 v118, v70
	v_mov_b32_e32 v119, v64
	v_fmac_f32_e32 v75, v58, v85
	v_mov_b32_e32 v114, v71
	v_mov_b32_e32 v115, v65
	v_pk_mul_f32 v[64:65], v[118:119], v[118:119]
	v_mov_b32_e32 v140, v137
	s_waitcnt lgkmcnt(1)
	v_fmac_f32_e32 v75, v31, v86
	v_pk_fma_f32 v[114:115], v[114:115], v[114:115], v[64:65]
	v_pk_mul_f32 v[64:65], v[140:141], v[70:71]
	s_waitcnt lgkmcnt(0)
	v_fmac_f32_e32 v75, v30, v90
	v_fmac_f32_e32 v75, v65, v87
	ds_read_b128 v[80:83], v77 offset:512
	ds_read_b128 v[84:87], v77 offset:528
	v_lshlrev_b32_e32 v119, 16, v133
	v_lshlrev_b32_e32 v118, 16, v135
	v_mov_b32_e32 v70, v138
	v_mov_b32_e32 v71, v142
	v_pk_mul_f32 v[70:71], v[70:71], v[118:119]
	v_fmac_f32_e32 v75, v64, v91
	s_waitcnt lgkmcnt(1)
	v_fma_f32 v79, v60, v80, 0
	v_and_b32_e32 v121, 0xffff0000, v133
	v_and_b32_e32 v120, 0xffff0000, v135
	v_mov_b32_e32 v142, v139
	v_fmac_f32_e32 v75, v71, v88
	s_waitcnt lgkmcnt(0)
	v_fmac_f32_e32 v79, v62, v84
	v_pk_mul_f32 v[72:73], v[142:143], v[120:121]
	v_fmac_f32_e32 v75, v70, v92
	v_fmac_f32_e32 v79, v61, v81
	v_add_f32_e32 v11, v94, v11
	v_fmac_f32_e32 v75, v73, v89
	v_fmac_f32_e32 v79, v63, v85
	v_add_f32_e32 v11, v95, v11
	v_fmac_f32_e32 v75, v72, v93
	v_fmac_f32_e32 v79, v66, v82
	ds_read_b128 v[88:91], v77 offset:576
	ds_read_b128 v[92:95], v77 offset:592
	v_fmac_f32_e32 v79, v68, v86
	v_fmac_f32_e32 v79, v67, v83
	v_fmac_f32_e32 v79, v69, v87
	s_waitcnt lgkmcnt(1)
	v_fmac_f32_e32 v79, v50, v88
	s_waitcnt lgkmcnt(0)
	v_fmac_f32_e32 v79, v52, v92
	v_fmac_f32_e32 v79, v51, v89
	v_fmac_f32_e32 v79, v53, v93
	v_fmac_f32_e32 v79, v54, v90
	ds_read_b128 v[80:83], v77 offset:640
	ds_read_b128 v[84:87], v77 offset:656
	v_fmac_f32_e32 v79, v56, v94
	v_fmac_f32_e32 v79, v55, v91
	v_fmac_f32_e32 v79, v57, v95
	s_waitcnt lgkmcnt(1)
	v_fmac_f32_e32 v79, v38, v80
	s_waitcnt lgkmcnt(0)
	v_fmac_f32_e32 v79, v40, v84
	v_fmac_f32_e32 v79, v39, v81
	v_fmac_f32_e32 v79, v41, v85
	v_fmac_f32_e32 v79, v44, v82
	ds_read_b128 v[88:91], v77 offset:704
	ds_read_b128 v[92:95], v77 offset:720
	v_fmac_f32_e32 v79, v46, v86
	v_fmac_f32_e32 v79, v45, v83
	v_fmac_f32_e32 v79, v47, v87
	s_waitcnt lgkmcnt(1)
	v_fmac_f32_e32 v79, v18, v88
	s_waitcnt lgkmcnt(0)
	v_fmac_f32_e32 v79, v20, v92
	v_fmac_f32_e32 v79, v19, v89
	v_fmac_f32_e32 v79, v21, v93
	v_fmac_f32_e32 v79, v24, v90
	ds_read_b128 v[80:83], v77 offset:768
	ds_read_b128 v[84:87], v77 offset:784
	v_fmac_f32_e32 v79, v26, v94
	v_fmac_f32_e32 v79, v25, v91
	v_fmac_f32_e32 v79, v27, v95
	s_waitcnt lgkmcnt(1)
	v_fmac_f32_e32 v79, v0, v80
	s_waitcnt lgkmcnt(0)
	v_fmac_f32_e32 v79, v2, v84
	v_fmac_f32_e32 v79, v1, v81
	v_fmac_f32_e32 v79, v3, v85
	v_fmac_f32_e32 v79, v14, v82
	ds_read_b128 v[88:91], v77 offset:832
	ds_read_b128 v[92:95], v77 offset:848
	v_fmac_f32_e32 v79, v16, v86
	v_fmac_f32_e32 v79, v15, v83
	v_fmac_f32_e32 v79, v17, v87
	s_waitcnt lgkmcnt(1)
	v_fmac_f32_e32 v79, v22, v88
	s_waitcnt lgkmcnt(0)
	v_fmac_f32_e32 v79, v28, v92
	v_fmac_f32_e32 v79, v23, v89
	v_fmac_f32_e32 v79, v29, v93
	v_fmac_f32_e32 v79, v42, v90
	ds_read_b128 v[80:83], v77 offset:896
	ds_read_b128 v[84:87], v77 offset:912
	v_fmac_f32_e32 v79, v48, v94
	v_fmac_f32_e32 v79, v43, v91
	v_fmac_f32_e32 v79, v49, v95
	s_waitcnt lgkmcnt(1)
	v_fmac_f32_e32 v79, v32, v80
	s_waitcnt lgkmcnt(0)
	v_fmac_f32_e32 v79, v34, v84
	v_fmac_f32_e32 v79, v33, v81
	v_fmac_f32_e32 v79, v35, v85
	v_fmac_f32_e32 v79, v37, v82
	ds_read_b128 v[88:91], v77 offset:960
	ds_read_b128 v[92:95], v77 offset:976
	v_fmac_f32_e32 v79, v36, v86
	v_fmac_f32_e32 v79, v59, v83
	v_fmac_f32_e32 v79, v58, v87
	s_waitcnt lgkmcnt(1)
	v_fmac_f32_e32 v79, v31, v88
	s_waitcnt lgkmcnt(0)
	v_fmac_f32_e32 v79, v30, v92
	v_fmac_f32_e32 v79, v65, v89
	ds_read_b128 v[82:85], v77 offset:1024
	ds_read_b128 v[86:89], v77 offset:1040
	v_add_f32_e32 v11, v113, v11
	v_fmac_f32_e32 v79, v64, v93
	v_add_f32_e32 v11, v112, v11
	s_waitcnt lgkmcnt(1)
	v_fma_f32 v81, v60, v82, 0
	s_waitcnt lgkmcnt(0)
	v_fmac_f32_e32 v81, v62, v86
	v_fmac_f32_e32 v79, v71, v90
	v_fmac_f32_e32 v81, v61, v83
	v_add_f32_e32 v11, v115, v11
	v_fmac_f32_e32 v79, v70, v94
	v_fmac_f32_e32 v81, v63, v87
	v_add_f32_e32 v11, v114, v11
	v_fmac_f32_e32 v79, v73, v91
	v_fmac_f32_e32 v81, v66, v84
	ds_read_b128 v[90:93], v77 offset:1088
	ds_read_b128 v[112:115], v77 offset:1104
	v_fmac_f32_e32 v81, v68, v88
	v_fmac_f32_e32 v81, v67, v85
	v_fmac_f32_e32 v81, v69, v89
	s_waitcnt lgkmcnt(1)
	v_fmac_f32_e32 v81, v50, v90
	s_waitcnt lgkmcnt(0)
	v_fmac_f32_e32 v81, v52, v112
	v_fmac_f32_e32 v81, v51, v91
	v_fmac_f32_e32 v81, v53, v113
	v_fmac_f32_e32 v81, v54, v92
	ds_read_b128 v[82:85], v77 offset:1152
	ds_read_b128 v[86:89], v77 offset:1168
	v_fmac_f32_e32 v81, v56, v114
	v_fmac_f32_e32 v81, v55, v93
	v_fmac_f32_e32 v81, v57, v115
	s_waitcnt lgkmcnt(1)
	v_fmac_f32_e32 v81, v38, v82
	s_waitcnt lgkmcnt(0)
	v_fmac_f32_e32 v81, v40, v86
	v_fmac_f32_e32 v81, v39, v83
	v_fmac_f32_e32 v81, v41, v87
	v_fmac_f32_e32 v81, v44, v84
	ds_read_b128 v[90:93], v77 offset:1216
	ds_read_b128 v[112:115], v77 offset:1232
	v_fmac_f32_e32 v81, v46, v88
	v_fmac_f32_e32 v81, v45, v85
	v_fmac_f32_e32 v81, v47, v89
	s_waitcnt lgkmcnt(1)
	v_fmac_f32_e32 v81, v18, v90
	s_waitcnt lgkmcnt(0)
	v_fmac_f32_e32 v81, v20, v112
	v_fmac_f32_e32 v81, v19, v91
	v_fmac_f32_e32 v81, v21, v113
	v_fmac_f32_e32 v81, v24, v92
	ds_read_b128 v[82:85], v77 offset:1280
	ds_read_b128 v[86:89], v77 offset:1296
	v_fmac_f32_e32 v81, v26, v114
	v_fmac_f32_e32 v81, v25, v93
	v_fmac_f32_e32 v81, v27, v115
	s_waitcnt lgkmcnt(1)
	v_fmac_f32_e32 v81, v0, v82
	s_waitcnt lgkmcnt(0)
	v_fmac_f32_e32 v81, v2, v86
	v_fmac_f32_e32 v81, v1, v83
	v_fmac_f32_e32 v81, v3, v87
	v_fmac_f32_e32 v81, v14, v84
	ds_read_b128 v[90:93], v77 offset:1344
	ds_read_b128 v[112:115], v77 offset:1360
	v_fmac_f32_e32 v81, v16, v88
	v_fmac_f32_e32 v81, v15, v85
	v_fmac_f32_e32 v81, v17, v89
	s_waitcnt lgkmcnt(1)
	v_fmac_f32_e32 v81, v22, v90
	s_waitcnt lgkmcnt(0)
	v_fmac_f32_e32 v81, v28, v112
	v_fmac_f32_e32 v81, v23, v91
	v_fmac_f32_e32 v81, v29, v113
	v_fmac_f32_e32 v81, v42, v92
	ds_read_b128 v[82:85], v77 offset:1408
	ds_read_b128 v[86:89], v77 offset:1424
	v_fmac_f32_e32 v81, v48, v114
	v_fmac_f32_e32 v81, v43, v93
	v_fmac_f32_e32 v81, v49, v115
	s_waitcnt lgkmcnt(1)
	v_fmac_f32_e32 v81, v32, v82
	s_waitcnt lgkmcnt(0)
	v_fmac_f32_e32 v81, v34, v86
	v_fmac_f32_e32 v81, v33, v83
	v_fmac_f32_e32 v81, v35, v87
	v_fmac_f32_e32 v81, v37, v84
	ds_read_b128 v[90:93], v77 offset:1472
	ds_read_b128 v[112:115], v77 offset:1488
	v_fmac_f32_e32 v81, v36, v88
	v_fmac_f32_e32 v81, v59, v85
	v_fmac_f32_e32 v81, v58, v89
	s_waitcnt lgkmcnt(1)
	v_fmac_f32_e32 v81, v31, v90
	s_waitcnt lgkmcnt(0)
	v_fmac_f32_e32 v81, v30, v112
	v_fmac_f32_e32 v81, v65, v91
	ds_read_b128 v[84:87], v77 offset:1536
	ds_read_b128 v[88:91], v77 offset:1552
	v_fmac_f32_e32 v81, v64, v113
	v_fmac_f32_e32 v81, v71, v92
	v_fmac_f32_e32 v81, v70, v114
	s_waitcnt lgkmcnt(1)
	v_fma_f32 v83, v60, v84, 0
	s_waitcnt lgkmcnt(0)
	v_fmac_f32_e32 v83, v62, v88
	v_fmac_f32_e32 v83, v61, v85
	v_fmac_f32_e32 v81, v73, v93
	v_fmac_f32_e32 v83, v63, v89
	v_fmac_f32_e32 v79, v72, v95
	v_fmac_f32_e32 v81, v72, v115
	v_fmac_f32_e32 v83, v66, v86
	ds_read_b128 v[92:95], v77 offset:1600
	ds_read_b128 v[112:115], v77 offset:1616
	v_fmac_f32_e32 v83, v68, v90
	v_fmac_f32_e32 v83, v67, v87
	v_fmac_f32_e32 v83, v69, v91
	s_waitcnt lgkmcnt(1)
	v_fmac_f32_e32 v83, v50, v92
	s_waitcnt lgkmcnt(0)
	v_fmac_f32_e32 v83, v52, v112
	v_fmac_f32_e32 v83, v51, v93
	v_fmac_f32_e32 v83, v53, v113
	v_fmac_f32_e32 v83, v54, v94
	ds_read_b128 v[84:87], v77 offset:1664
	ds_read_b128 v[88:91], v77 offset:1680
	v_fmac_f32_e32 v83, v56, v114
	v_fmac_f32_e32 v83, v55, v95
	v_fmac_f32_e32 v83, v57, v115
	s_waitcnt lgkmcnt(1)
	v_fmac_f32_e32 v83, v38, v84
	s_waitcnt lgkmcnt(0)
	v_fmac_f32_e32 v83, v40, v88
	v_fmac_f32_e32 v83, v39, v85
	v_fmac_f32_e32 v83, v41, v89
	v_fmac_f32_e32 v83, v44, v86
	ds_read_b128 v[92:95], v77 offset:1728
	ds_read_b128 v[112:115], v77 offset:1744
	v_fmac_f32_e32 v83, v46, v90
	v_fmac_f32_e32 v83, v45, v87
	v_fmac_f32_e32 v83, v47, v91
	s_waitcnt lgkmcnt(1)
	v_fmac_f32_e32 v83, v18, v92
	s_waitcnt lgkmcnt(0)
	v_fmac_f32_e32 v83, v20, v112
	v_fmac_f32_e32 v83, v19, v93
	v_fmac_f32_e32 v83, v21, v113
	v_fmac_f32_e32 v83, v24, v94
	ds_read_b128 v[84:87], v77 offset:1792
	ds_read_b128 v[88:91], v77 offset:1808
	v_fmac_f32_e32 v83, v26, v114
	v_fmac_f32_e32 v83, v25, v95
	v_fmac_f32_e32 v83, v27, v115
	s_waitcnt lgkmcnt(1)
	v_fmac_f32_e32 v83, v0, v84
	s_waitcnt lgkmcnt(0)
	v_fmac_f32_e32 v83, v2, v88
	v_fmac_f32_e32 v83, v1, v85
	v_fmac_f32_e32 v83, v3, v89
	v_fmac_f32_e32 v83, v14, v86
	ds_read_b128 v[92:95], v77 offset:1856
	ds_read_b128 v[112:115], v77 offset:1872
	v_fmac_f32_e32 v83, v16, v90
	v_fmac_f32_e32 v83, v15, v87
	v_fmac_f32_e32 v83, v17, v91
	s_waitcnt lgkmcnt(1)
	v_fmac_f32_e32 v83, v22, v92
	s_waitcnt lgkmcnt(0)
	v_fmac_f32_e32 v83, v28, v112
	v_fmac_f32_e32 v83, v23, v93
	v_fmac_f32_e32 v83, v29, v113
	v_fmac_f32_e32 v83, v42, v94
	ds_read_b128 v[84:87], v77 offset:1920
	ds_read_b128 v[88:91], v77 offset:1936
	v_fmac_f32_e32 v83, v48, v114
	v_fmac_f32_e32 v83, v43, v95
	v_fmac_f32_e32 v83, v49, v115
	s_waitcnt lgkmcnt(1)
	v_fmac_f32_e32 v83, v32, v84
	s_waitcnt lgkmcnt(0)
	v_fmac_f32_e32 v83, v34, v88
	v_fmac_f32_e32 v83, v33, v85
	v_fmac_f32_e32 v83, v35, v89
	v_fmac_f32_e32 v83, v37, v86
	ds_read_b128 v[92:95], v77 offset:1984
	ds_read_b128 v[112:115], v77 offset:2000
	v_fmac_f32_e32 v83, v36, v90
	v_fmac_f32_e32 v83, v59, v87
	v_fmac_f32_e32 v83, v58, v91
	s_waitcnt lgkmcnt(1)
	v_fmac_f32_e32 v83, v31, v92
	s_waitcnt lgkmcnt(0)
	v_fmac_f32_e32 v83, v30, v112
	v_fmac_f32_e32 v83, v65, v93
	ds_read_b128 v[86:89], v77 offset:2048
	ds_read_b128 v[90:93], v77 offset:2064
	v_mov_b32_e32 v124, v120
	v_mov_b32_e32 v125, v118
	v_fmac_f32_e32 v83, v64, v113
	s_waitcnt lgkmcnt(1)
	v_fma_f32 v85, v60, v86, 0
	v_mov_b32_e32 v122, v121
	v_mov_b32_e32 v123, v119
	v_pk_mul_f32 v[118:119], v[124:125], v[124:125]
	v_fmac_f32_e32 v83, v71, v94
	s_waitcnt lgkmcnt(0)
	v_fmac_f32_e32 v85, v62, v90
	v_pk_fma_f32 v[118:119], v[122:123], v[122:123], v[118:119]
	v_fmac_f32_e32 v83, v70, v114
	v_fmac_f32_e32 v85, v61, v87
	v_add_f32_e32 v11, v119, v11
	v_fmac_f32_e32 v83, v73, v95
	v_fmac_f32_e32 v85, v63, v91
	v_add_f32_e32 v11, v118, v11
	v_fmac_f32_e32 v83, v72, v115
	v_fmac_f32_e32 v85, v66, v88
	ds_read_b128 v[112:115], v77 offset:2112
	ds_read_b128 v[116:119], v77 offset:2128
	v_fmac_f32_e32 v85, v68, v92
	v_fmac_f32_e32 v85, v67, v89
	v_fmac_f32_e32 v85, v69, v93
	s_waitcnt lgkmcnt(1)
	v_fmac_f32_e32 v85, v50, v112
	s_waitcnt lgkmcnt(0)
	v_fmac_f32_e32 v85, v52, v116
	v_fmac_f32_e32 v85, v51, v113
	v_fmac_f32_e32 v85, v53, v117
	v_fmac_f32_e32 v85, v54, v114
	ds_read_b128 v[86:89], v77 offset:2176
	ds_read_b128 v[90:93], v77 offset:2192
	v_fmac_f32_e32 v85, v56, v118
	v_fmac_f32_e32 v85, v55, v115
	v_fmac_f32_e32 v85, v57, v119
	s_waitcnt lgkmcnt(1)
	v_fmac_f32_e32 v85, v38, v86
	s_waitcnt lgkmcnt(0)
	v_fmac_f32_e32 v85, v40, v90
	v_fmac_f32_e32 v85, v39, v87
	v_fmac_f32_e32 v85, v41, v91
	v_fmac_f32_e32 v85, v44, v88
	ds_read_b128 v[112:115], v77 offset:2240
	ds_read_b128 v[116:119], v77 offset:2256
	v_fmac_f32_e32 v85, v46, v92
	v_fmac_f32_e32 v85, v45, v89
	v_fmac_f32_e32 v85, v47, v93
	s_waitcnt lgkmcnt(1)
	v_fmac_f32_e32 v85, v18, v112
	s_waitcnt lgkmcnt(0)
	v_fmac_f32_e32 v85, v20, v116
	v_fmac_f32_e32 v85, v19, v113
	v_fmac_f32_e32 v85, v21, v117
	v_fmac_f32_e32 v85, v24, v114
	ds_read_b128 v[86:89], v77 offset:2304
	ds_read_b128 v[90:93], v77 offset:2320
	v_fmac_f32_e32 v85, v26, v118
	v_fmac_f32_e32 v85, v25, v115
	v_fmac_f32_e32 v85, v27, v119
	s_waitcnt lgkmcnt(1)
	v_fmac_f32_e32 v85, v0, v86
	s_waitcnt lgkmcnt(0)
	v_fmac_f32_e32 v85, v2, v90
	v_fmac_f32_e32 v85, v1, v87
	v_fmac_f32_e32 v85, v3, v91
	v_fmac_f32_e32 v85, v14, v88
	ds_read_b128 v[112:115], v77 offset:2368
	ds_read_b128 v[116:119], v77 offset:2384
	v_fmac_f32_e32 v85, v16, v92
	v_fmac_f32_e32 v85, v15, v89
	v_fmac_f32_e32 v85, v17, v93
	s_waitcnt lgkmcnt(1)
	v_fmac_f32_e32 v85, v22, v112
	s_waitcnt lgkmcnt(0)
	v_fmac_f32_e32 v85, v28, v116
	v_fmac_f32_e32 v85, v23, v113
	v_fmac_f32_e32 v85, v29, v117
	v_fmac_f32_e32 v85, v42, v114
	ds_read_b128 v[86:89], v77 offset:2432
	ds_read_b128 v[90:93], v77 offset:2448
	v_fmac_f32_e32 v85, v48, v118
	v_fmac_f32_e32 v85, v43, v115
	v_fmac_f32_e32 v85, v49, v119
	s_waitcnt lgkmcnt(1)
	v_fmac_f32_e32 v85, v32, v86
	s_waitcnt lgkmcnt(0)
	v_fmac_f32_e32 v85, v34, v90
	v_fmac_f32_e32 v85, v33, v87
	v_fmac_f32_e32 v85, v35, v91
	v_fmac_f32_e32 v85, v37, v88
	ds_read_b128 v[112:115], v77 offset:2496
	ds_read_b128 v[116:119], v77 offset:2512
	v_fmac_f32_e32 v85, v36, v92
	v_fmac_f32_e32 v85, v59, v89
	v_fmac_f32_e32 v85, v58, v93
	ds_read_b128 v[88:91], v77 offset:2560
	ds_read_b128 v[92:95], v77 offset:2576
	s_waitcnt lgkmcnt(3)
	v_fmac_f32_e32 v85, v31, v112
	s_waitcnt lgkmcnt(2)
	v_fmac_f32_e32 v85, v30, v116
	v_fmac_f32_e32 v85, v65, v113
	v_fmac_f32_e32 v85, v64, v117
	s_waitcnt lgkmcnt(1)
	v_fma_f32 v87, v60, v88, 0
	v_fmac_f32_e32 v85, v71, v114
	s_waitcnt lgkmcnt(0)
	v_fmac_f32_e32 v87, v62, v92
	v_fmac_f32_e32 v85, v70, v118
	v_fmac_f32_e32 v87, v61, v89
	v_fmac_f32_e32 v85, v73, v115
	v_fmac_f32_e32 v87, v63, v93
	v_fmac_f32_e32 v85, v72, v119
	v_fmac_f32_e32 v87, v66, v90
	ds_read_b128 v[112:115], v77 offset:2624
	ds_read_b128 v[116:119], v77 offset:2640
	v_fmac_f32_e32 v87, v68, v94
	v_fmac_f32_e32 v87, v67, v91
	v_fmac_f32_e32 v87, v69, v95
	s_waitcnt lgkmcnt(1)
	v_fmac_f32_e32 v87, v50, v112
	s_waitcnt lgkmcnt(0)
	v_fmac_f32_e32 v87, v52, v116
	v_fmac_f32_e32 v87, v51, v113
	v_fmac_f32_e32 v87, v53, v117
	v_fmac_f32_e32 v87, v54, v114
	ds_read_b128 v[88:91], v77 offset:2688
	ds_read_b128 v[92:95], v77 offset:2704
	v_fmac_f32_e32 v87, v56, v118
	v_fmac_f32_e32 v87, v55, v115
	v_fmac_f32_e32 v87, v57, v119
	s_waitcnt lgkmcnt(1)
	v_fmac_f32_e32 v87, v38, v88
	s_waitcnt lgkmcnt(0)
	v_fmac_f32_e32 v87, v40, v92
	v_fmac_f32_e32 v87, v39, v89
	v_fmac_f32_e32 v87, v41, v93
	v_fmac_f32_e32 v87, v44, v90
	ds_read_b128 v[112:115], v77 offset:2752
	ds_read_b128 v[116:119], v77 offset:2768
	v_fmac_f32_e32 v87, v46, v94
	v_fmac_f32_e32 v87, v45, v91
	v_fmac_f32_e32 v87, v47, v95
	s_waitcnt lgkmcnt(1)
	v_fmac_f32_e32 v87, v18, v112
	s_waitcnt lgkmcnt(0)
	v_fmac_f32_e32 v87, v20, v116
	v_fmac_f32_e32 v87, v19, v113
	v_fmac_f32_e32 v87, v21, v117
	v_fmac_f32_e32 v87, v24, v114
	ds_read_b128 v[88:91], v77 offset:2816
	ds_read_b128 v[92:95], v77 offset:2832
	v_fmac_f32_e32 v87, v26, v118
	v_fmac_f32_e32 v87, v25, v115
	v_fmac_f32_e32 v87, v27, v119
	s_waitcnt lgkmcnt(1)
	v_fmac_f32_e32 v87, v0, v88
	s_waitcnt lgkmcnt(0)
	v_fmac_f32_e32 v87, v2, v92
	v_fmac_f32_e32 v87, v1, v89
	v_fmac_f32_e32 v87, v3, v93
	v_fmac_f32_e32 v87, v14, v90
	ds_read_b128 v[112:115], v77 offset:2880
	ds_read_b128 v[116:119], v77 offset:2896
	v_fmac_f32_e32 v87, v16, v94
	v_fmac_f32_e32 v87, v15, v91
	v_fmac_f32_e32 v87, v17, v95
	s_waitcnt lgkmcnt(1)
	v_fmac_f32_e32 v87, v22, v112
	s_waitcnt lgkmcnt(0)
	v_fmac_f32_e32 v87, v28, v116
	v_fmac_f32_e32 v87, v23, v113
	v_fmac_f32_e32 v87, v29, v117
	v_fmac_f32_e32 v87, v42, v114
	ds_read_b128 v[88:91], v77 offset:2944
	ds_read_b128 v[92:95], v77 offset:2960
	v_fmac_f32_e32 v87, v48, v118
	v_fmac_f32_e32 v87, v43, v115
	v_fmac_f32_e32 v87, v49, v119
	s_waitcnt lgkmcnt(1)
	v_fmac_f32_e32 v87, v32, v88
	s_waitcnt lgkmcnt(0)
	v_fmac_f32_e32 v87, v34, v92
	v_fmac_f32_e32 v87, v33, v89
	v_fmac_f32_e32 v87, v35, v93
	v_fmac_f32_e32 v87, v37, v90
	ds_read_b128 v[112:115], v77 offset:3008
	ds_read_b128 v[116:119], v77 offset:3024
	v_fmac_f32_e32 v87, v36, v94
	v_fmac_f32_e32 v87, v59, v91
	v_fmac_f32_e32 v87, v58, v95
	ds_read_b128 v[90:93], v77 offset:3072
	ds_read_b128 v[120:123], v77 offset:3088
	s_waitcnt lgkmcnt(3)
	v_fmac_f32_e32 v87, v31, v112
	s_waitcnt lgkmcnt(2)
	v_fmac_f32_e32 v87, v30, v116
	v_fmac_f32_e32 v87, v65, v113
	v_fmac_f32_e32 v87, v64, v117
	s_waitcnt lgkmcnt(1)
	v_fma_f32 v89, v60, v90, 0
	v_fmac_f32_e32 v87, v71, v114
	s_waitcnt lgkmcnt(0)
	v_fmac_f32_e32 v89, v62, v120
	v_fmac_f32_e32 v87, v70, v118
	v_fmac_f32_e32 v89, v61, v91
	v_fmac_f32_e32 v87, v73, v115
	v_fmac_f32_e32 v89, v63, v121
	v_fmac_f32_e32 v87, v72, v119
	v_fmac_f32_e32 v89, v66, v92
	ds_read_b128 v[112:115], v77 offset:3136
	ds_read_b128 v[116:119], v77 offset:3152
	v_fmac_f32_e32 v89, v68, v122
	v_fmac_f32_e32 v89, v67, v93
	v_fmac_f32_e32 v89, v69, v123
	s_waitcnt lgkmcnt(1)
	v_fmac_f32_e32 v89, v50, v112
	s_waitcnt lgkmcnt(0)
	v_fmac_f32_e32 v89, v52, v116
	v_fmac_f32_e32 v89, v51, v113
	v_fmac_f32_e32 v89, v53, v117
	v_fmac_f32_e32 v89, v54, v114
	ds_read_b128 v[90:93], v77 offset:3200
	ds_read_b128 v[120:123], v77 offset:3216
	v_fmac_f32_e32 v89, v56, v118
	v_fmac_f32_e32 v89, v55, v115
	v_fmac_f32_e32 v89, v57, v119
	s_waitcnt lgkmcnt(1)
	v_fmac_f32_e32 v89, v38, v90
	s_waitcnt lgkmcnt(0)
	v_fmac_f32_e32 v89, v40, v120
	v_fmac_f32_e32 v89, v39, v91
	v_fmac_f32_e32 v89, v41, v121
	v_fmac_f32_e32 v89, v44, v92
	ds_read_b128 v[112:115], v77 offset:3264
	ds_read_b128 v[116:119], v77 offset:3280
	v_fmac_f32_e32 v89, v46, v122
	v_fmac_f32_e32 v89, v45, v93
	v_fmac_f32_e32 v89, v47, v123
	s_waitcnt lgkmcnt(1)
	v_fmac_f32_e32 v89, v18, v112
	s_waitcnt lgkmcnt(0)
	v_fmac_f32_e32 v89, v20, v116
	v_fmac_f32_e32 v89, v19, v113
	v_fmac_f32_e32 v89, v21, v117
	v_fmac_f32_e32 v89, v24, v114
	ds_read_b128 v[90:93], v77 offset:3328
	ds_read_b128 v[120:123], v77 offset:3344
	v_fmac_f32_e32 v89, v26, v118
	v_fmac_f32_e32 v89, v25, v115
	v_fmac_f32_e32 v89, v27, v119
	s_waitcnt lgkmcnt(1)
	v_fmac_f32_e32 v89, v0, v90
	s_waitcnt lgkmcnt(0)
	v_fmac_f32_e32 v89, v2, v120
	v_fmac_f32_e32 v89, v1, v91
	v_fmac_f32_e32 v89, v3, v121
	v_fmac_f32_e32 v89, v14, v92
	ds_read_b128 v[112:115], v77 offset:3392
	ds_read_b128 v[116:119], v77 offset:3408
	v_fmac_f32_e32 v89, v16, v122
	v_fmac_f32_e32 v89, v15, v93
	v_fmac_f32_e32 v89, v17, v123
	s_waitcnt lgkmcnt(1)
	v_fmac_f32_e32 v89, v22, v112
	s_waitcnt lgkmcnt(0)
	v_fmac_f32_e32 v89, v28, v116
	v_fmac_f32_e32 v89, v23, v113
	v_fmac_f32_e32 v89, v29, v117
	v_fmac_f32_e32 v89, v42, v114
	ds_read_b128 v[90:93], v77 offset:3456
	ds_read_b128 v[120:123], v77 offset:3472
	v_fmac_f32_e32 v89, v48, v118
	v_fmac_f32_e32 v89, v43, v115
	v_fmac_f32_e32 v89, v49, v119
	s_waitcnt lgkmcnt(1)
	v_fmac_f32_e32 v89, v32, v90
	s_waitcnt lgkmcnt(0)
	v_fmac_f32_e32 v89, v34, v120
	v_fmac_f32_e32 v89, v33, v91
	v_fmac_f32_e32 v89, v35, v121
	v_fmac_f32_e32 v89, v37, v92
	ds_read_b128 v[112:115], v77 offset:3520
	ds_read_b128 v[116:119], v77 offset:3536
	v_fmac_f32_e32 v89, v36, v122
	v_fmac_f32_e32 v89, v59, v93
	v_fmac_f32_e32 v89, v58, v123
	ds_read_b128 v[92:95], v77 offset:3584
	ds_read_b128 v[120:123], v77 offset:3600
	s_waitcnt lgkmcnt(3)
	v_fmac_f32_e32 v89, v31, v112
	s_waitcnt lgkmcnt(2)
	v_fmac_f32_e32 v89, v30, v116
	v_fmac_f32_e32 v89, v65, v113
	v_fmac_f32_e32 v89, v64, v117
	s_waitcnt lgkmcnt(1)
	v_fma_f32 v91, v60, v92, 0
	v_fmac_f32_e32 v89, v71, v114
	s_waitcnt lgkmcnt(0)
	v_fmac_f32_e32 v91, v62, v120
	v_fmac_f32_e32 v89, v70, v118
	v_fmac_f32_e32 v91, v61, v93
	v_fmac_f32_e32 v89, v73, v115
	v_fmac_f32_e32 v91, v63, v121
	v_fmac_f32_e32 v89, v72, v119
	v_fmac_f32_e32 v91, v66, v94
	ds_read_b128 v[112:115], v77 offset:3648
	ds_read_b128 v[116:119], v77 offset:3664
	v_fmac_f32_e32 v91, v68, v122
	v_fmac_f32_e32 v91, v67, v95
	v_fmac_f32_e32 v91, v69, v123
	s_waitcnt lgkmcnt(1)
	v_fmac_f32_e32 v91, v50, v112
	s_waitcnt lgkmcnt(0)
	v_fmac_f32_e32 v91, v52, v116
	v_fmac_f32_e32 v91, v51, v113
	v_fmac_f32_e32 v91, v53, v117
	v_fmac_f32_e32 v91, v54, v114
	ds_read_b128 v[92:95], v77 offset:3712
	ds_read_b128 v[120:123], v77 offset:3728
	v_fmac_f32_e32 v91, v56, v118
	v_fmac_f32_e32 v91, v55, v115
	v_fmac_f32_e32 v91, v57, v119
	s_waitcnt lgkmcnt(1)
	v_fmac_f32_e32 v91, v38, v92
	s_waitcnt lgkmcnt(0)
	v_fmac_f32_e32 v91, v40, v120
	v_fmac_f32_e32 v91, v39, v93
	v_fmac_f32_e32 v91, v41, v121
	v_fmac_f32_e32 v91, v44, v94
	ds_read_b128 v[112:115], v77 offset:3776
	ds_read_b128 v[116:119], v77 offset:3792
	v_fmac_f32_e32 v91, v46, v122
	v_fmac_f32_e32 v91, v45, v95
	v_fmac_f32_e32 v91, v47, v123
	s_waitcnt lgkmcnt(1)
	v_fmac_f32_e32 v91, v18, v112
	s_waitcnt lgkmcnt(0)
	v_fmac_f32_e32 v91, v20, v116
	v_fmac_f32_e32 v91, v19, v113
	v_fmac_f32_e32 v91, v21, v117
	v_fmac_f32_e32 v91, v24, v114
	ds_read_b128 v[92:95], v77 offset:3840
	ds_read_b128 v[120:123], v77 offset:3856
	v_fmac_f32_e32 v91, v26, v118
	v_fmac_f32_e32 v91, v25, v115
	v_fmac_f32_e32 v91, v27, v119
	s_waitcnt lgkmcnt(1)
	v_fmac_f32_e32 v91, v0, v92
	s_waitcnt lgkmcnt(0)
	v_fmac_f32_e32 v91, v2, v120
	v_fmac_f32_e32 v91, v1, v93
	v_fmac_f32_e32 v91, v3, v121
	v_fmac_f32_e32 v91, v14, v94
	ds_read_b128 v[112:115], v77 offset:3904
	ds_read_b128 v[116:119], v77 offset:3920
	v_fmac_f32_e32 v91, v16, v122
	v_fmac_f32_e32 v91, v15, v95
	v_fmac_f32_e32 v91, v17, v123
	s_waitcnt lgkmcnt(1)
	v_fmac_f32_e32 v91, v22, v112
	s_waitcnt lgkmcnt(0)
	v_fmac_f32_e32 v91, v28, v116
	v_fmac_f32_e32 v91, v23, v113
	v_fmac_f32_e32 v91, v29, v117
	v_fmac_f32_e32 v91, v42, v114
	ds_read_b128 v[92:95], v77 offset:3968
	ds_read_b128 v[120:123], v77 offset:3984
	v_fmac_f32_e32 v91, v48, v118
	v_fmac_f32_e32 v91, v43, v115
	v_fmac_f32_e32 v91, v49, v119
	s_waitcnt lgkmcnt(1)
	v_fmac_f32_e32 v91, v32, v92
	s_waitcnt lgkmcnt(0)
	v_fmac_f32_e32 v91, v34, v120
	v_fmac_f32_e32 v91, v33, v93
	v_fmac_f32_e32 v91, v35, v121
	v_fmac_f32_e32 v91, v37, v94
	ds_read_b128 v[112:115], v77 offset:4032
	ds_read_b128 v[116:119], v77 offset:4048
	v_fmac_f32_e32 v91, v36, v122
	v_fmac_f32_e32 v91, v59, v95
	v_fmac_f32_e32 v91, v58, v123
	s_waitcnt lgkmcnt(1)
	v_fmac_f32_e32 v91, v31, v112
	s_waitcnt lgkmcnt(0)
	v_fmac_f32_e32 v91, v30, v116
	v_fmac_f32_e32 v91, v65, v113
	v_fmac_f32_e32 v91, v64, v117
	v_fmac_f32_e32 v91, v71, v114
	v_fmac_f32_e32 v91, v70, v118
	v_fmac_f32_e32 v91, v73, v115
	v_fmac_f32_e32 v91, v72, v119
	ds_bpermute_b32 v76, v169, v11
	ds_bpermute_b32 v78, v169, v75
	ds_bpermute_b32 v80, v169, v79
	ds_bpermute_b32 v82, v169, v81
	ds_bpermute_b32 v84, v169, v83
	ds_bpermute_b32 v86, v169, v85
	ds_bpermute_b32 v88, v169, v87
	ds_bpermute_b32 v90, v169, v89
	ds_bpermute_b32 v93, v169, v91
	v_mov_b32_e32 v92, 0
	s_cbranch_scc1 .LBB0_1714
	ds_read_b128 v[112:115], v77 offset:4096
	ds_read_b128 v[116:119], v77 offset:4112
	ds_read_b128 v[120:123], v77 offset:4160
	ds_read_b128 v[124:127], v77 offset:4176
	s_waitcnt lgkmcnt(3)
	v_fma_f32 v92, v60, v112, 0
	s_waitcnt lgkmcnt(2)
	v_fmac_f32_e32 v92, v62, v116
	v_fmac_f32_e32 v92, v61, v113
	v_fmac_f32_e32 v92, v63, v117
	v_fmac_f32_e32 v92, v66, v114
	v_fmac_f32_e32 v92, v68, v118
	v_fmac_f32_e32 v92, v67, v115
	v_fmac_f32_e32 v92, v69, v119
	s_waitcnt lgkmcnt(1)
	v_fmac_f32_e32 v92, v50, v120
	s_waitcnt lgkmcnt(0)
	v_fmac_f32_e32 v92, v52, v124
	v_fmac_f32_e32 v92, v51, v121
	v_fmac_f32_e32 v92, v53, v125
	v_fmac_f32_e32 v92, v54, v122
	ds_read_b128 v[112:115], v77 offset:4224
	ds_read_b128 v[116:119], v77 offset:4240
	v_fmac_f32_e32 v92, v56, v126
	v_fmac_f32_e32 v92, v55, v123
	v_fmac_f32_e32 v92, v57, v127
	s_waitcnt lgkmcnt(1)
	v_fmac_f32_e32 v92, v38, v112
	s_waitcnt lgkmcnt(0)
	v_fmac_f32_e32 v92, v40, v116
	v_fmac_f32_e32 v92, v39, v113
	v_fmac_f32_e32 v92, v41, v117
	v_fmac_f32_e32 v92, v44, v114
	ds_read_b128 v[120:123], v77 offset:4288
	ds_read_b128 v[124:127], v77 offset:4304
	v_fmac_f32_e32 v92, v46, v118
	v_fmac_f32_e32 v92, v45, v115
	v_fmac_f32_e32 v92, v47, v119
	s_waitcnt lgkmcnt(1)
	v_fmac_f32_e32 v92, v18, v120
	s_waitcnt lgkmcnt(0)
	v_fmac_f32_e32 v92, v20, v124
	v_fmac_f32_e32 v92, v19, v121
	v_fmac_f32_e32 v92, v21, v125
	v_fmac_f32_e32 v92, v24, v122
	ds_read_b128 v[112:115], v77 offset:4352
	ds_read_b128 v[116:119], v77 offset:4368
	v_fmac_f32_e32 v92, v26, v126
	v_fmac_f32_e32 v92, v25, v123
	v_fmac_f32_e32 v92, v27, v127
	s_waitcnt lgkmcnt(1)
	v_fmac_f32_e32 v92, v0, v112
	s_waitcnt lgkmcnt(0)
	v_fmac_f32_e32 v92, v2, v116
	v_fmac_f32_e32 v92, v1, v113
	v_fmac_f32_e32 v92, v3, v117
	v_fmac_f32_e32 v92, v14, v114
	ds_read_b128 v[120:123], v77 offset:4416
	ds_read_b128 v[124:127], v77 offset:4432
	v_fmac_f32_e32 v92, v16, v118
	v_fmac_f32_e32 v92, v15, v115
	v_fmac_f32_e32 v92, v17, v119
	s_waitcnt lgkmcnt(1)
	v_fmac_f32_e32 v92, v22, v120
	s_waitcnt lgkmcnt(0)
	v_fmac_f32_e32 v92, v28, v124
	v_fmac_f32_e32 v92, v23, v121
	v_fmac_f32_e32 v92, v29, v125
	v_fmac_f32_e32 v92, v42, v122
	ds_read_b128 v[112:115], v77 offset:4480
	ds_read_b128 v[116:119], v77 offset:4496
	v_fmac_f32_e32 v92, v48, v126
	v_fmac_f32_e32 v92, v43, v123
	v_fmac_f32_e32 v92, v49, v127
	s_waitcnt lgkmcnt(1)
	v_fmac_f32_e32 v92, v32, v112
	s_waitcnt lgkmcnt(0)
	v_fmac_f32_e32 v92, v34, v116
	v_fmac_f32_e32 v92, v33, v113
	v_mov_b32_e32 v94, v118
	v_mov_b32_e32 v95, v114
	ds_read_b128 v[120:123], v77 offset:4544
	ds_read_b128 v[124:127], v77 offset:4560
	v_fmac_f32_e32 v92, v35, v117
	v_pk_mul_f32 v[94:95], v[36:37], v[94:95]
	v_mov_b32_e32 v114, v119
	v_add_f32_e32 v92, v95, v92
	v_add_f32_e32 v92, v94, v92
	v_pk_mul_f32 v[94:95], v[58:59], v[114:115]
	s_nop 0
	v_add_f32_e32 v92, v95, v92
	v_add_f32_e32 v92, v94, v92
	s_waitcnt lgkmcnt(0)
	v_mov_b32_e32 v94, v124
	v_mov_b32_e32 v95, v120
	v_pk_mul_f32 v[94:95], v[30:31], v[94:95]
	v_mov_b32_e32 v120, v125
	v_add_f32_e32 v92, v95, v92
	v_add_f32_e32 v92, v94, v92
	v_pk_mul_f32 v[94:95], v[64:65], v[120:121]
	s_nop 0
	v_add_f32_e32 v92, v95, v92
	v_add_f32_e32 v92, v94, v92
	v_mov_b32_e32 v94, v126
	v_mov_b32_e32 v95, v122
	v_pk_mul_f32 v[94:95], v[70:71], v[94:95]
	v_mov_b32_e32 v122, v127
	v_add_f32_e32 v92, v95, v92
	v_add_f32_e32 v92, v94, v92
	v_pk_mul_f32 v[94:95], v[72:73], v[122:123]
	s_nop 0
	v_add_f32_e32 v92, v95, v92
	v_add_f32_e32 v92, v94, v92
	ds_bpermute_b32 v94, v169, v92
	s_waitcnt lgkmcnt(0)
	v_add_f32_e32 v92, v92, v94

.LBB0_1769:
	s_waitcnt lgkmcnt(0)
	v_add_f32_e32 v7, v7, v75
	v_fmamk_f32 v7, v7, 0x3c000000, v158
	v_lshlrev_b64 v[148:149], 11, v[8:9]
	v_mul_f32_e32 v8, 0x4b800000, v7
	v_cmp_gt_f32_e32 vcc, s92, v7
	v_and_b32_e32 v76, 31, v0
	v_lshlrev_b32_e32 v147, 2, v1
	v_cndmask_b32_e32 v7, v7, v8, vcc
	v_rsq_f32_e32 v7, v7
	v_mov_b32_e32 v1, v145
	s_and_b32 s0, s80, 7
	s_lshl_b32 s0, s0, 2
	v_mul_f32_e32 v8, 0x45800000, v7
	v_cndmask_b32_e32 v7, v7, v8, vcc
	v_mul_f32_e32 v8, 0x3e0293ee, v7
	v_pk_mul_f32 v[14:15], v[14:15], v[8:9] op_sel_hi:[1,0]
	v_pk_mul_f32 v[16:17], v[16:17], v[8:9] op_sel_hi:[1,0]
	v_cvt_pk_bf16_f32 v114, v14, v15
	v_pk_mul_f32 v[12:13], v[12:13], v[8:9] op_sel_hi:[1,0]
	v_pk_mul_f32 v[14:15], v[24:25], v[8:9] op_sel_hi:[1,0]
	v_pk_mul_f32 v[10:11], v[10:11], v[8:9] op_sel_hi:[1,0]
	v_cvt_pk_bf16_f32 v112, v16, v17
	v_pk_mul_f32 v[16:17], v[22:23], v[8:9] op_sel_hi:[1,0]
	v_cvt_pk_bf16_f32 v116, v12, v13
	v_cvt_pk_bf16_f32 v117, v14, v15
	v_cvt_pk_bf16_f32 v118, v10, v11
	v_pk_mul_f32 v[10:11], v[26:27], v[8:9] op_sel_hi:[1,0]
	v_pk_mul_f32 v[12:13], v[32:33], v[8:9] op_sel_hi:[1,0]
	v_pk_mul_f32 v[14:15], v[28:29], v[8:9] op_sel_hi:[1,0]
	v_cvt_pk_bf16_f32 v119, v16, v17
	v_pk_mul_f32 v[16:17], v[30:31], v[8:9] op_sel_hi:[1,0]
	v_cvt_pk_bf16_f32 v120, v10, v11
	v_cvt_pk_bf16_f32 v121, v12, v13
	v_cvt_pk_bf16_f32 v122, v14, v15
	v_pk_mul_f32 v[10:11], v[36:37], v[8:9] op_sel_hi:[1,0]
	v_pk_mul_f32 v[12:13], v[40:41], v[8:9] op_sel_hi:[1,0]
	v_pk_mul_f32 v[14:15], v[34:35], v[8:9] op_sel_hi:[1,0]
	v_cvt_pk_bf16_f32 v123, v16, v17
	v_pk_mul_f32 v[16:17], v[38:39], v[8:9] op_sel_hi:[1,0]
	v_cvt_pk_bf16_f32 v124, v10, v11
	v_cvt_pk_bf16_f32 v125, v12, v13
	v_cvt_pk_bf16_f32 v126, v14, v15
	v_pk_mul_f32 v[10:11], v[44:45], v[8:9] op_sel_hi:[1,0]
	v_pk_mul_f32 v[12:13], v[48:49], v[8:9] op_sel_hi:[1,0]
	v_pk_mul_f32 v[14:15], v[42:43], v[8:9] op_sel_hi:[1,0]
	v_cvt_pk_bf16_f32 v127, v16, v17
	v_pk_mul_f32 v[16:17], v[46:47], v[8:9] op_sel_hi:[1,0]
	v_cvt_pk_bf16_f32 v128, v10, v11
	v_cvt_pk_bf16_f32 v129, v12, v13
	v_cvt_pk_bf16_f32 v130, v14, v15
	v_pk_mul_f32 v[10:11], v[52:53], v[8:9] op_sel_hi:[1,0]
	v_pk_mul_f32 v[12:13], v[56:57], v[8:9] op_sel_hi:[1,0]
	v_pk_mul_f32 v[14:15], v[50:51], v[8:9] op_sel_hi:[1,0]
	v_cvt_pk_bf16_f32 v131, v16, v17
	v_pk_mul_f32 v[16:17], v[54:55], v[8:9] op_sel_hi:[1,0]
	v_cvt_pk_bf16_f32 v132, v10, v11
	v_cvt_pk_bf16_f32 v133, v12, v13
	v_cvt_pk_bf16_f32 v134, v14, v15
	v_pk_mul_f32 v[10:11], v[60:61], v[8:9] op_sel_hi:[1,0]
	v_pk_mul_f32 v[12:13], v[64:65], v[8:9] op_sel_hi:[1,0]
	v_pk_mul_f32 v[14:15], v[58:59], v[8:9] op_sel_hi:[1,0]
	v_pk_mul_f32 v[20:21], v[20:21], v[8:9] op_sel_hi:[1,0]
	v_pk_mul_f32 v[18:19], v[18:19], v[8:9] op_sel_hi:[1,0]
	v_cvt_pk_bf16_f32 v135, v16, v17
	v_pk_mul_f32 v[16:17], v[62:63], v[8:9] op_sel_hi:[1,0]
	v_cvt_pk_bf16_f32 v136, v10, v11
	v_cvt_pk_bf16_f32 v137, v12, v13
	v_cvt_pk_bf16_f32 v138, v14, v15
	v_pk_mul_f32 v[10:11], v[68:69], v[8:9] op_sel_hi:[1,0]
	v_pk_mul_f32 v[12:13], v[70:71], v[8:9] op_sel_hi:[1,0]
	v_pk_mul_f32 v[14:15], v[66:67], v[8:9] op_sel_hi:[1,0]
	v_pk_mul_f32 v[8:9], v[72:73], v[8:9] op_sel_hi:[1,0]
	v_add_u32_e32 v7, 0x2000, v2
	v_cvt_pk_bf16_f32 v143, v8, v9
	v_lshrrev_b32_e32 v8, 4, v0
	v_and_b32_e32 v0, 7, v0
	v_lshlrev_b32_e32 v0, 4, v0
	v_cvt_pk_bf16_f32 v142, v14, v15
	v_lshrrev_b32_e32 v7, 8, v7
	v_lshl_add_u64 v[0:1], v[4:5], 0, v[0:1]
	v_mov_b32_e32 v14, v145
	v_mov_b32_e32 v15, v145
	v_cvt_pk_bf16_f32 v113, v20, v21
	v_cvt_pk_bf16_f32 v115, v18, v19
	v_cvt_pk_bf16_f32 v139, v16, v17
	v_cvt_pk_bf16_f32 v140, v10, v11
	v_cvt_pk_bf16_f32 v141, v12, v13
	v_mul_lo_u32 v179, v8, s52
	v_and_b32_e32 v177, 0xf0, v2
	v_mul_i32_i24_e32 v180, 0x110, v7
	v_mul_lo_u32 v176, v6, s97
	v_and_b32_e32 v178, 0x70, v2
	v_lshl_add_u64 v[150:151], s[88:89], 0, v[0:1]
	v_lshl_add_u64 v[152:153], s[88:89], 0, v[2:3]
	v_mov_b32_e32 v0, v145
	v_mov_b32_e32 v1, v145
	v_mov_b32_e32 v2, v145
	v_mov_b32_e32 v3, v145
	v_mov_b32_e32 v4, v145
	v_mov_b32_e32 v5, v145
	v_mov_b32_e32 v6, v145
	v_mov_b32_e32 v7, v145
	v_mov_b32_e32 v8, v145
	v_mov_b32_e32 v9, v145
	v_mov_b32_e32 v10, v145
	v_mov_b32_e32 v11, v145
	v_mov_b32_e32 v12, v145
	v_mov_b32_e32 v13, v145
	v_mov_b64_e32 v[30:31], v[14:15]
	v_mov_b64_e32 v[46:47], v[14:15]
	v_mov_b64_e32 v[62:63], v[14:15]
	v_and_b32_e32 v173, 0xffffffe0, v74
	s_or_b32 s14, s0, 3
	v_or_b32_e32 v175, 31, v74
	v_mul_u32_u24_e32 v174, 0x110, v76
	v_mul_u32_u24_e32 v171, 0x90, v76
	s_mov_b32 s15, 0
	v_mov_b32_e32 v154, 0xf149f2ca
	v_mov_b32_e32 v170, 0
	v_mov_b64_e32 v[28:29], v[12:13]
	v_mov_b64_e32 v[26:27], v[10:11]
	v_mov_b64_e32 v[24:25], v[8:9]
	v_mov_b64_e32 v[22:23], v[6:7]
	v_mov_b64_e32 v[20:21], v[4:5]
	v_mov_b64_e32 v[18:19], v[2:3]
	v_mov_b64_e32 v[16:17], v[0:1]
	v_mov_b64_e32 v[44:45], v[12:13]
	v_mov_b64_e32 v[42:43], v[10:11]
	v_mov_b64_e32 v[40:41], v[8:9]
	v_mov_b64_e32 v[38:39], v[6:7]
	v_mov_b64_e32 v[36:37], v[4:5]
	v_mov_b64_e32 v[34:35], v[2:3]
	v_mov_b64_e32 v[32:33], v[0:1]
	v_mov_b64_e32 v[60:61], v[12:13]
	v_mov_b64_e32 v[58:59], v[10:11]
	v_mov_b64_e32 v[56:57], v[8:9]
	v_mov_b64_e32 v[54:55], v[6:7]
	v_mov_b64_e32 v[52:53], v[4:5]
	v_mov_b64_e32 v[50:51], v[2:3]
	v_mov_b64_e32 v[48:49], v[0:1]
	s_branch .LBB0_1772
